# attention queues: heavy diff items (q-blocks descending) interleaved with light diff items taken q-blocks ascending
# speedup vs baseline: 1.0212x; 1.0212x over previous
.LBB0_840:
	s_andn2_b64 vcc, exec, s[38:39]
	s_cbranch_vccnz .LBB0_842
	s_add_i32 s4, s54, -12
	s_lshr_b32 s30, s4, 1
	s_andn2_b32 s50, 0x7f, s30
	s_bitcmp0_b32 s4, 0
	s_cselect_b32 s50, s50, s30
	v_readlane_b32 s4, v250, 18
	v_readlane_b32 s5, v250, 19
	s_cselect_b32 s6, 2, 1
	s_cselect_b32 s30, 3, 0
	s_and_b64 s[4:5], s[4:5], exec
	s_cselect_b32 s6, s30, s6
	s_mov_b64 s[4:5], 0
	s_mov_b32 s55, s71
